# GQA attention loop: QK K-fragment LDS reads double-buffered with counted waits (on top of PV counted waits)
# baseline (speedup 1.0000x reference)
; __device__ __forceinline__ void finishSM(f32x16& p0, f32x16& p1, float alpha, float& l_reg, bf16x8& pa0, bf16x8& pa1, bf16x8& pa2, bf16x8& pa3) {
; #pragma unroll
;   for (int r = 0; r < 16; ++r) p1[r] = __builtin_amdgcn_exp2f(p1[r]);
;   float ps = 0;
; #pragma unroll
;   for (int r = 0; r < 16; ++r) ps += p0[r];
; #pragma unroll
;   for (int r = 0; r < 16; ++r) ps += p1[r];
;   { auto rr = __builtin_amdgcn_permlane32_swap(__float_as_uint(ps), __float_as_uint(ps), false, false);
;     ps = __uint_as_float(rr[0]) + __uint_as_float(rr[1]); }
;   l_reg = l_reg * alpha + ps;
;     ...
;   PK4(p0, 0, pa0); PK4(p0, 8, pa1); PK4(p1, 0, pa2); PK4(p1, 8, pa3);
;     ...
; }
; template <bool MLA>
; __device__ __forceinline__ void qkt(f32x16& p0, f32x16& p1, const char* Ks, const char* KRs, const bf16x8* qr, const char* qrl, const f32x16& negm, int r32, int hi) {
; #pragma unroll
;   for (int d0 = 0; d0 < 8; ++d0) { int cb = (d0 * 16 + hi * 8) * 2;
;     bf16x8 b0 = *reinterpret_cast<const bf16x8*>(Ks + KSWZ(r32, cb));
;     bf16x8 b1 = *reinterpret_cast<const bf16x8*>(Ks + KSWZ(32 + r32, cb));
;     if (d0 == 0) { p0 = __builtin_amdgcn_mfma_f32_32x32x16_bf16(b0, qr[0], negm, 0, 0, 0); p1 = __builtin_amdgcn_mfma_f32_32x32x16_bf16(b1, qr[0], negm, 0, 0, 0); }
;     else { p0 = __builtin_amdgcn_mfma_f32_32x32x16_bf16(b0, qr[d0], p0, 0, 0, 0); p1 = __builtin_amdgcn_mfma_f32_32x32x16_bf16(b1, qr[d0], p1, 0, 0, 0); } }
.LBB0_125:
	s_mov_b32 s13, s16
	s_mov_b32 s16, s23
	s_lshl_b32 s8, s17, 14
	s_add_i32 s23, s8, 0
	s_add_i32 s32, s23, s14
	s_lshl_b32 s19, s13, 14
	s_add_i32 s8, s19, 0
	v_add_u32_e32 v98, s8, v199
	ds_read_b128 v[220:223], v98 offset:57344
	ds_read_b128 v[98:101], v98 offset:49152
	v_add_u32_e32 v246, s8, v198
	ds_read_b128 v[238:241], v246 offset:57344
	ds_read_b128 v[242:245], v246 offset:49152
	v_add_u32_e32 v201, s8, v197
	s_add_u32 vcc_lo, s2, s62
	s_addc_u32 vcc_hi, s3, s63
	s_add_i32 m0, s32, 0xc000
	v_lshl_add_u64 v[250:251], v[168:169], 0, vcc
	global_load_lds_dwordx4 v[250:251], off
	v_exp_f32_e32 v203, v82
	v_add_f32_e32 v82, 0, v217
	v_add_f32_e32 v82, v219, v82
	s_waitcnt lgkmcnt(2)
	v_mfma_f32_32x32x16_bf16 v[114:129], v[98:101], v[158:161], v[66:81]
	v_add_f32_e32 v82, v215, v82
	v_add_f32_e32 v82, v218, v82
	v_add_f32_e32 v82, v214, v82
	v_add_f32_e32 v82, v216, v82
	v_add_f32_e32 v82, v212, v82
	v_add_f32_e32 v82, v213, v82
	v_add_f32_e32 v82, v209, v82
	v_mfma_f32_32x32x16_bf16 v[98:113], v[220:223], v[158:161], v[66:81]
	ds_read_b128 v[220:223], v201 offset:57344
	ds_read_b128 v[224:227], v201 offset:49152
	v_add_u32_e32 v201, s8, v196
	s_add_u32 vcc_lo, s2, 0x1c3c1600
	s_addc_u32 vcc_hi, s3, 0
	s_mov_b32 m0, s32
	v_lshl_add_u64 v[250:251], v[0:1], 0, vcc
	global_load_lds_dwordx4 v[250:251], off
	v_add_f32_e32 v82, v211, v82
	v_add_f32_e32 v82, v208, v82
	v_add_f32_e32 v82, v210, v82
	v_add_f32_e32 v82, v205, v82
	v_add_f32_e32 v82, v207, v82
	s_waitcnt lgkmcnt(2)
	v_mfma_f32_32x32x16_bf16 v[98:113], v[238:241], v[154:157], v[98:113]
	v_add_f32_e32 v82, v204, v82
	v_add_f32_e32 v82, v206, v82
	v_add_f32_e32 v82, v203, v82
	v_exp_f32_e32 v228, v91
	v_exp_f32_e32 v229, v92
	v_exp_f32_e32 v234, v93
	v_exp_f32_e32 v235, v94
	v_mfma_f32_32x32x16_bf16 v[114:129], v[242:245], v[154:157], v[114:129]
	ds_read_b128 v[238:241], v201 offset:57344
	ds_read_b128 v[242:245], v201 offset:49152
	v_add_u32_e32 v201, s8, v195
	s_add_u32 vcc_lo, s2, s62
	s_addc_u32 vcc_hi, s3, s63
	s_add_i32 m0, s32, 0xc400
	v_lshl_add_u64 v[250:251], v[170:171], 0, vcc
	global_load_lds_dwordx4 v[250:251], off
	v_exp_f32_e32 v236, v95
	v_exp_f32_e32 v237, v96
	v_exp_f32_e32 v97, v97
	s_lshl_b32 s24, s16, 14
	s_waitcnt lgkmcnt(2)
	v_mfma_f32_32x32x16_bf16 v[98:113], v[220:223], v[150:153], v[98:113]
	v_mfma_f32_32x32x16_bf16 v[114:129], v[224:227], v[150:153], v[114:129]
	ds_read_b128 v[220:223], v201 offset:57344
	ds_read_b128 v[224:227], v201 offset:49152
	v_add_u32_e32 v201, s8, v183
	s_add_u32 vcc_lo, s2, 0x1c3c1680
	s_addc_u32 vcc_hi, s3, 0
	s_add_i32 m0, s32, 0x400
	v_lshl_add_u64 v[250:251], v[0:1], 0, vcc
	global_load_lds_dwordx4 v[250:251], off
	s_waitcnt lgkmcnt(2)
	v_mfma_f32_32x32x16_bf16 v[98:113], v[238:241], v[146:149], v[98:113]
	v_mfma_f32_32x32x16_bf16 v[114:129], v[242:245], v[146:149], v[114:129]
	ds_read_b128 v[238:241], v201 offset:57344
	ds_read_b128 v[242:245], v201 offset:49152
	v_add_u32_e32 v201, s8, v193
	s_waitcnt lgkmcnt(2)
	v_mfma_f32_32x32x16_bf16 v[98:113], v[220:223], v[142:145], v[98:113]
	v_mfma_f32_32x32x16_bf16 v[114:129], v[224:227], v[142:145], v[114:129]
	ds_read_b128 v[220:223], v201 offset:57344
	ds_read_b128 v[224:227], v201 offset:49152
	v_add_u32_e32 v201, s8, v194
	s_waitcnt lgkmcnt(2)
	v_mfma_f32_32x32x16_bf16 v[98:113], v[238:241], v[138:141], v[98:113]
	v_mfma_f32_32x32x16_bf16 v[114:129], v[242:245], v[138:141], v[114:129]
	ds_read_b128 v[238:241], v201 offset:57344
	ds_read_b128 v[242:245], v201 offset:49152
	s_waitcnt lgkmcnt(2)
	v_mfma_f32_32x32x16_bf16 v[98:113], v[220:223], v[134:137], v[98:113]
	v_mfma_f32_32x32x16_bf16 v[114:129], v[224:227], v[134:137], v[114:129]
	s_waitcnt lgkmcnt(0)
	v_mfma_f32_32x32x16_bf16 v[98:113], v[238:241], v[130:133], v[98:113]
	v_exp_f32_e32 v220, v83
	v_exp_f32_e32 v221, v84
	v_exp_f32_e32 v222, v85
	v_exp_f32_e32 v223, v86
	v_add_f32_e32 v82, v220, v82
	v_add_f32_e32 v82, v221, v82
	v_add_f32_e32 v82, v222, v82
	v_mfma_f32_32x32x16_bf16 v[114:129], v[242:245], v[130:133], v[114:129]
	v_exp_f32_e32 v224, v87
	v_exp_f32_e32 v225, v88
	v_exp_f32_e32 v226, v89
	v_exp_f32_e32 v227, v90
	v_add_f32_e32 v82, v223, v82
	v_add_f32_e32 v82, v224, v82
	v_add_f32_e32 v82, v225, v82
	v_add_f32_e32 v82, v226, v82
	v_add_f32_e32 v82, v227, v82
	v_add_f32_e32 v82, v228, v82
	v_add_f32_e32 v82, v229, v82
	v_add_f32_e32 v82, v234, v82
	v_add_f32_e32 v82, v235, v82
	v_add_f32_e32 v82, v236, v82
	v_add_f32_e32 v82, v237, v82
	v_add_f32_e32 v201, v97, v82
	v_cvt_pk_bf16_f32 v82, v217, v219
	v_cvt_pk_bf16_f32 v83, v215, v218
	v_cvt_pk_bf16_f32 v84, v214, v216
	v_cvt_pk_bf16_f32 v85, v212, v213
	v_cvt_pk_bf16_f32 v86, v209, v211
	v_cvt_pk_bf16_f32 v87, v208, v210
	v_cvt_pk_bf16_f32 v88, v205, v207
	v_cvt_pk_bf16_f32 v89, v204, v206
	v_cvt_pk_bf16_f32 v90, v203, v220
	v_cvt_pk_bf16_f32 v91, v221, v222
	v_cvt_pk_bf16_f32 v92, v223, v224
	v_cvt_pk_bf16_f32 v93, v225, v226
	v_cvt_pk_bf16_f32 v94, v227, v228
	v_cvt_pk_bf16_f32 v95, v229, v234
	v_cvt_pk_bf16_f32 v96, v235, v236
	v_cvt_pk_bf16_f32 v97, v237, v97
	v_add_u32_e32 v203, s24, v182
	ds_read_b64_tr_b16 v[204:205], v203 offset:0
	ds_read_b64_tr_b16 v[206:207], v203 offset:0x800
	ds_read_b64_tr_b16 v[208:209], v203 offset:0x1000
	ds_read_b64_tr_b16 v[210:211], v203 offset:0x1800
	ds_read_b64_tr_b16 v[212:213], v203 offset:0x2000
	ds_read_b64_tr_b16 v[214:215], v203 offset:0x2800
	ds_read_b64_tr_b16 v[216:217], v203 offset:0x3000
	ds_read_b64_tr_b16 v[218:219], v203 offset:0x3800
	s_waitcnt lgkmcnt(0)
; #define SBAR() __builtin_amdgcn_sched_barrier(0)
; __device__ __forceinline__ float max3f(float a, float b, float c) { return __builtin_fmaxf(__builtin_fmaxf(a, b), c); }
; template <bool FIRST, bool MLA>
; __device__ __forceinline__ void partialSM(f32x16& p0, f32x16& p1, f32x16& negm, float& m_reg, float& alpha) {
;   float a = max3f(p0[0], p0[1], p1[0]), b = max3f(p0[2], p0[3], p1[1]); a = max3f(a, p1[2], p1[3]);
; #pragma unroll
;   for (int r = 4; r < 16; r += 4) { a = max3f(a, p0[r], p0[r + 1]); b = max3f(b, p0[r + 2], p0[r + 3]); a = max3f(a, p1[r], p1[r + 1]); b = max3f(b, p1[r + 2], p1[r + 3]); }
;   float pmax = fmaxf(a, b);
;   { auto rr = __builtin_amdgcn_permlane32_swap(__float_as_uint(pmax), __float_as_uint(pmax), false, false);
;     pmax = fmaxf(__uint_as_float(rr[0]), __uint_as_float(rr[1])); }
;   alpha = 1.f;
;   if constexpr (MLA) {
;     if (FIRST) m_reg = pmax;
;     else if (!__builtin_expect(__all(pmax - m_reg <= THR2), 1)) { const float mn = fmaxf(m_reg, pmax); alpha = __builtin_amdgcn_exp2f(m_reg - mn); m_reg = mn; }
; #pragma unroll
;     for (int r = 0; r < 16; ++r) { p0[r] -= m_reg; p1[r] -= m_reg; }
;   } else
;   if (FIRST || __builtin_expect(__any(pmax > THR2), 0)) {
; template <int D0> __device__ __forceinline__ void pv_one(f32x16& od, int vb, bf16x8 pa0, bf16x8 pa1, bf16x8 pa2, bf16x8 pa3) {
;   const s16x4 l0 = tr_read<v_rd_off(D0, 0, 0)>(vb), h0 = tr_read<v_rd_off(D0, 0, 1)>(vb), l1 = tr_read<v_rd_off(D0, 1, 0)>(vb), h1 = tr_read<v_rd_off(D0, 1, 1)>(vb);
;   const s16x4 l2 = tr_read<v_rd_off(D0, 2, 0)>(vb), h2 = tr_read<v_rd_off(D0, 2, 1)>(vb), l3 = tr_read<v_rd_off(D0, 3, 0)>(vb), h3 = tr_read<v_rd_off(D0, 3, 1)>(vb);
;   asm volatile("s_waitcnt lgkmcnt(0)" ::: "memory"); SBAR();
;     ...
;   od = __builtin_amdgcn_mfma_f32_32x32x16_bf16(pa0, PK(l0, h0), od, 0, 0, 0);
;   od = __builtin_amdgcn_mfma_f32_32x32x16_bf16(pa1, PK(l1, h1), od, 0, 0, 0);
;   od = __builtin_amdgcn_mfma_f32_32x32x16_bf16(pa2, PK(l2, h2), od, 0, 0, 0);
;   od = __builtin_amdgcn_mfma_f32_32x32x16_bf16(pa3, PK(l3, h3), od, 0, 0, 0);
;     ...
; }
; __device__ __forceinline__ void pv_d0(f32x16* o, int vb, bf16x8 pa0, bf16x8 pa1, bf16x8 pa2, bf16x8 pa3) {
;   pv_one<0>(o[0], vb, pa0, pa1, pa2, pa3); pv_one<1>(o[1], vb, pa0, pa1, pa2, pa3); pv_one<2>(o[2], vb, pa0, pa1, pa2, pa3); pv_one<3>(o[3], vb, pa0, pa1, pa2, pa3);
	v_mov_b32_e32 v202, v201
	s_nop 1
	v_permlane32_swap_b32_e32 v201, v202
	v_permlane32_swap_b32_e32 v82, v84
	v_permlane32_swap_b32_e32 v83, v85
	v_permlane32_swap_b32_e32 v86, v88
	v_permlane32_swap_b32_e32 v87, v89
	v_permlane32_swap_b32_e32 v90, v92
	v_permlane32_swap_b32_e32 v91, v93
	v_permlane32_swap_b32_e32 v94, v96
	v_permlane32_swap_b32_e32 v95, v97
	v_mfma_f32_32x32x16_bf16 v[2:17], v[82:85], v[204:207], v[2:17]
	ds_read_b64_tr_b16 v[204:205], v203 offset:0x200
	ds_read_b64_tr_b16 v[206:207], v203 offset:0xa00
	v_mfma_f32_32x32x16_bf16 v[2:17], v[86:89], v[208:211], v[2:17]
	ds_read_b64_tr_b16 v[208:209], v203 offset:0x1200
	ds_read_b64_tr_b16 v[210:211], v203 offset:0x1a00
	v_mfma_f32_32x32x16_bf16 v[2:17], v[90:93], v[212:215], v[2:17]
	ds_read_b64_tr_b16 v[212:213], v203 offset:0x2200
	ds_read_b64_tr_b16 v[214:215], v203 offset:0x2a00
	v_mfma_f32_32x32x16_bf16 v[2:17], v[94:97], v[216:219], v[2:17]
	ds_read_b64_tr_b16 v[216:217], v203 offset:0x3200
	ds_read_b64_tr_b16 v[218:219], v203 offset:0x3a00
	s_waitcnt lgkmcnt(6)
	v_mfma_f32_32x32x16_bf16 v[50:65], v[82:85], v[204:207], v[50:65]
	ds_read_b64_tr_b16 v[204:205], v203 offset:0x400
	ds_read_b64_tr_b16 v[206:207], v203 offset:0xc00
	s_waitcnt lgkmcnt(6)
	v_mfma_f32_32x32x16_bf16 v[50:65], v[86:89], v[208:211], v[50:65]
	ds_read_b64_tr_b16 v[208:209], v203 offset:0x1400
	ds_read_b64_tr_b16 v[210:211], v203 offset:0x1c00
	s_waitcnt lgkmcnt(6)
	v_mfma_f32_32x32x16_bf16 v[50:65], v[90:93], v[212:215], v[50:65]
	ds_read_b64_tr_b16 v[212:213], v203 offset:0x2400
	ds_read_b64_tr_b16 v[214:215], v203 offset:0x2c00
	s_waitcnt lgkmcnt(6)
	v_mfma_f32_32x32x16_bf16 v[50:65], v[94:97], v[216:219], v[50:65]
	ds_read_b64_tr_b16 v[216:217], v203 offset:0x3400
	ds_read_b64_tr_b16 v[218:219], v203 offset:0x3c00
	s_waitcnt lgkmcnt(6)
	v_mfma_f32_32x32x16_bf16 v[34:49], v[82:85], v[204:207], v[34:49]
	ds_read_b64_tr_b16 v[204:205], v203 offset:0x600
	ds_read_b64_tr_b16 v[206:207], v203 offset:0xe00
	s_waitcnt lgkmcnt(6)
	v_mfma_f32_32x32x16_bf16 v[34:49], v[86:89], v[208:211], v[34:49]
	ds_read_b64_tr_b16 v[208:209], v203 offset:0x1600
	ds_read_b64_tr_b16 v[210:211], v203 offset:0x1e00
	s_waitcnt lgkmcnt(6)
	v_mfma_f32_32x32x16_bf16 v[34:49], v[90:93], v[212:215], v[34:49]
	ds_read_b64_tr_b16 v[212:213], v203 offset:0x2600
	ds_read_b64_tr_b16 v[214:215], v203 offset:0x2e00
	s_waitcnt lgkmcnt(6)
	v_mfma_f32_32x32x16_bf16 v[34:49], v[94:97], v[216:219], v[34:49]
	ds_read_b64_tr_b16 v[216:217], v203 offset:0x3600
	ds_read_b64_tr_b16 v[218:219], v203 offset:0x3e00
	s_waitcnt lgkmcnt(6)
	v_mfma_f32_32x32x16_bf16 v[18:33], v[82:85], v[204:207], v[18:33]
	v_max_f32_e32 v82, v115, v115
	v_max_f32_e32 v83, v114, v114
	v_max_f32_e32 v82, v83, v82
	v_max3_f32 v83, v116, v117, v99
	v_max3_f32 v82, v82, v98, v100
	v_max3_f32 v82, v82, v101, v118
	v_max3_f32 v83, v83, v120, v121
	s_waitcnt lgkmcnt(4)
	v_mfma_f32_32x32x16_bf16 v[18:33], v[86:89], v[208:211], v[18:33]
	v_max3_f32 v82, v82, v119, v102
	v_max3_f32 v83, v83, v104, v105
	v_max3_f32 v82, v82, v103, v122
	v_max3_f32 v83, v83, v124, v125
	v_max3_f32 v82, v82, v123, v106
	v_max3_f32 v83, v83, v108, v109
	v_max3_f32 v82, v82, v107, v126
	s_waitcnt lgkmcnt(2)
	v_mfma_f32_32x32x16_bf16 v[18:33], v[90:93], v[212:215], v[18:33]
	v_max3_f32 v83, v83, v128, v129
	v_max3_f32 v82, v82, v127, v110
	v_max3_f32 v83, v83, v112, v113
	v_max3_f32 v82, v82, v111, v83
	v_mov_b32_e32 v83, v82
	s_nop 1
	v_permlane32_swap_b32_e32 v82, v83
	s_waitcnt lgkmcnt(0)
	v_mfma_f32_32x32x16_bf16 v[18:33], v[94:97], v[216:219], v[18:33]
	v_max_f32_e32 v83, v83, v83
	v_max_f32_e32 v82, v82, v82
	v_max_f32_e32 v82, v82, v83
	v_cmp_lt_f32_e32 vcc, s40, v82
	s_cbranch_vccnz .LBB0_137
	v_mov_b32_e32 v203, 1.0
	v_cmp_gt_f32_e32 vcc, 1.0, v203
	s_cbranch_vccz .LBB0_130

; #define SBAR() __builtin_amdgcn_sched_barrier(0)
; #define WAIT_BAR() do { asm volatile("s_waitcnt vmcnt(0)" ::: "memory"); __syncthreads(); } while (0)
; #define RESC(a) do { if (__any((a) < 1.f)) { if (hi == 0) al_l[r32] = (a); asm volatile("s_waitcnt lgkmcnt(0)" ::: "memory"); \
;     _Pragma("unroll") for (int d = 0; d < 4; ++d) _Pragma("unroll") for (int r = 0; r < 16; ++r) o[d][r] *= al_l[crow(r, hi)]; } } while (0)
; #define ROT() do { const int t_ = s_prev; s_prev = s_cur; s_cur = s_next; s_next = t_; } while (0)
; __device__ __forceinline__ void finishSM(f32x16& p0, f32x16& p1, float alpha, float& l_reg, bf16x8& pa0, bf16x8& pa1, bf16x8& pa2, bf16x8& pa3) {
; #pragma unroll
;   for (int r = 0; r < 16; ++r) p1[r] = __builtin_amdgcn_exp2f(p1[r]);
;   float ps = 0;
; #pragma unroll
;   for (int r = 0; r < 16; ++r) ps += p0[r];
; #pragma unroll
;   for (int r = 0; r < 16; ++r) ps += p1[r];
;   { auto rr = __builtin_amdgcn_permlane32_swap(__float_as_uint(ps), __float_as_uint(ps), false, false);
;     ps = __uint_as_float(rr[0]) + __uint_as_float(rr[1]); }
;   l_reg = l_reg * alpha + ps;
;     ...
;   PK4(p0, 0, pa0); PK4(p0, 8, pa1); PK4(p1, 0, pa2); PK4(p1, 8, pa3);
;     ...
; }
; template <bool MLA>
; __device__ __forceinline__ void qkt(f32x16& p0, f32x16& p1, const char* Ks, const char* KRs, const bf16x8* qr, const char* qrl, const f32x16& negm, int r32, int hi) {
; #pragma unroll
;   for (int d0 = 0; d0 < 8; ++d0) { int cb = (d0 * 16 + hi * 8) * 2;
;     bf16x8 b0 = *reinterpret_cast<const bf16x8*>(Ks + KSWZ(r32, cb));
;     bf16x8 b1 = *reinterpret_cast<const bf16x8*>(Ks + KSWZ(32 + r32, cb));
;     if (d0 == 0) { p0 = __builtin_amdgcn_mfma_f32_32x32x16_bf16(b0, qr[0], negm, 0, 0, 0); p1 = __builtin_amdgcn_mfma_f32_32x32x16_bf16(b1, qr[0], negm, 0, 0, 0); }
;     else { p0 = __builtin_amdgcn_mfma_f32_32x32x16_bf16(b0, qr[d0], p0, 0, 0, 0); p1 = __builtin_amdgcn_mfma_f32_32x32x16_bf16(b1, qr[d0], p1, 0, 0, 0); } }
; template <bool MLA> ...
;     ...
;     RESC(alB); WAIT_BAR(); ROT();
;     SBAR(); DMA_TILE(j + 2, s_next); SBAR();
;     qkt<MLA>(pA0, pA1, K_lds + s_cur * SHM_K, KR_lds + s_cur * SHM_KR, qr, qrl, negm, r32, hi);
;     finishSM(pB0, pB1, alB, l_reg, pa0, pa1, pa2, pa3);
.LBB0_130:
	s_waitcnt vmcnt(0)
	v_exp_f32_e32 v208, v114
	v_exp_f32_e32 v209, v115
	v_exp_f32_e32 v210, v116
	v_exp_f32_e32 v211, v117
	v_exp_f32_e32 v212, v118
	v_exp_f32_e32 v213, v119
	v_exp_f32_e32 v214, v120
	v_exp_f32_e32 v215, v121
	v_exp_f32_e32 v216, v122
	v_exp_f32_e32 v217, v123
	v_exp_f32_e32 v218, v124
	v_exp_f32_e32 v219, v125
	v_exp_f32_e32 v220, v126
	v_exp_f32_e32 v221, v127
	v_exp_f32_e32 v222, v128
	v_exp_f32_e32 v223, v129
	s_waitcnt vmcnt(0)
	s_barrier
	s_add_i32 s24, s15, s24
	v_add_u32_e32 v82, s23, v199
	ds_read_b128 v[172:175], v82 offset:57344
	ds_read_b128 v[82:85], v82 offset:49152
	v_add_u32_e32 v246, s23, v198
	ds_read_b128 v[238:241], v246 offset:57344
	ds_read_b128 v[242:245], v246 offset:49152
	v_add_u32_e32 v176, s23, v197
	s_add_u32 vcc_lo, s2, s74
	s_addc_u32 vcc_hi, s3, s75
	s_add_i32 m0, s24, 0xc000
	v_lshl_add_u64 v[250:251], v[168:169], 0, vcc
	global_load_lds_dwordx4 v[250:251], off
	v_exp_f32_e32 v177, v103
	v_exp_f32_e32 v224, v108
	v_exp_f32_e32 v225, v109
	s_waitcnt lgkmcnt(2)
	v_mfma_f32_32x32x16_bf16 v[114:129], v[82:85], v[158:161], v[66:81]
	v_exp_f32_e32 v226, v110
	v_exp_f32_e32 v227, v111
	v_exp_f32_e32 v112, v112
	v_exp_f32_e32 v113, v113
	v_mfma_f32_32x32x16_bf16 v[82:97], v[172:175], v[158:161], v[66:81]
	ds_read_b128 v[172:175], v176 offset:57344
	ds_read_b128 v[204:207], v176 offset:49152
	v_add_u32_e32 v176, s23, v196
	s_add_u32 vcc_lo, s2, 0x1c421600
	s_addc_u32 vcc_hi, s3, 0
	s_mov_b32 m0, s24
	v_lshl_add_u64 v[250:251], v[0:1], 0, vcc
	global_load_lds_dwordx4 v[250:251], off
	s_waitcnt lgkmcnt(2)
	v_mfma_f32_32x32x16_bf16 v[82:97], v[238:241], v[154:157], v[82:97]
	v_mfma_f32_32x32x16_bf16 v[114:129], v[242:245], v[154:157], v[114:129]
	ds_read_b128 v[238:241], v176 offset:57344
	ds_read_b128 v[242:245], v176 offset:49152
	v_add_u32_e32 v176, s23, v195
	s_add_u32 vcc_lo, s2, s74
	s_addc_u32 vcc_hi, s3, s75
	s_add_i32 m0, s24, 0xc400
	v_lshl_add_u64 v[250:251], v[170:171], 0, vcc
	global_load_lds_dwordx4 v[250:251], off
	s_waitcnt lgkmcnt(2)
	v_mfma_f32_32x32x16_bf16 v[82:97], v[172:175], v[150:153], v[82:97]
	v_mfma_f32_32x32x16_bf16 v[114:129], v[204:207], v[150:153], v[114:129]
	ds_read_b128 v[172:175], v176 offset:57344
	ds_read_b128 v[204:207], v176 offset:49152
	v_add_u32_e32 v176, s23, v183
	s_add_u32 vcc_lo, s2, 0x1c421680
	s_addc_u32 vcc_hi, s3, 0
	s_add_i32 m0, s24, 0x400
	v_lshl_add_u64 v[250:251], v[0:1], 0, vcc
	global_load_lds_dwordx4 v[250:251], off
	s_waitcnt lgkmcnt(2)
	v_mfma_f32_32x32x16_bf16 v[82:97], v[238:241], v[146:149], v[82:97]
	v_mfma_f32_32x32x16_bf16 v[114:129], v[242:245], v[146:149], v[114:129]
	ds_read_b128 v[238:241], v176 offset:57344
	ds_read_b128 v[242:245], v176 offset:49152
	v_add_u32_e32 v176, s23, v193
	s_waitcnt lgkmcnt(2)
	v_mfma_f32_32x32x16_bf16 v[82:97], v[172:175], v[142:145], v[82:97]
	v_mfma_f32_32x32x16_bf16 v[114:129], v[204:207], v[142:145], v[114:129]
	ds_read_b128 v[172:175], v176 offset:57344
	ds_read_b128 v[204:207], v176 offset:49152
	v_add_u32_e32 v176, s23, v194
	s_waitcnt lgkmcnt(2)
	v_mfma_f32_32x32x16_bf16 v[82:97], v[238:241], v[138:141], v[82:97]
	v_mfma_f32_32x32x16_bf16 v[114:129], v[242:245], v[138:141], v[114:129]
	ds_read_b128 v[238:241], v176 offset:57344
	ds_read_b128 v[242:245], v176 offset:49152
	s_waitcnt lgkmcnt(2)
	v_mfma_f32_32x32x16_bf16 v[82:97], v[172:175], v[134:137], v[82:97]
	v_mfma_f32_32x32x16_bf16 v[114:129], v[204:207], v[134:137], v[114:129]
	v_exp_f32_e32 v176, v102
	s_waitcnt lgkmcnt(0)
	v_mfma_f32_32x32x16_bf16 v[82:97], v[238:241], v[130:133], v[82:97]
	v_exp_f32_e32 v172, v98
	v_add_f32_e32 v98, 0, v208
	v_add_f32_e32 v98, v209, v98
	v_add_f32_e32 v98, v210, v98
	v_add_f32_e32 v98, v211, v98
	v_add_f32_e32 v98, v212, v98
	v_add_f32_e32 v98, v213, v98
	v_add_f32_e32 v98, v214, v98
	v_add_f32_e32 v98, v215, v98
	v_add_f32_e32 v98, v216, v98
	v_add_f32_e32 v98, v217, v98
	v_add_f32_e32 v98, v218, v98
	v_add_f32_e32 v98, v219, v98
	v_add_f32_e32 v98, v220, v98
	v_exp_f32_e32 v173, v99
	v_add_f32_e32 v98, v221, v98
	v_exp_f32_e32 v174, v100
	v_add_f32_e32 v98, v222, v98
	v_exp_f32_e32 v175, v101
	v_add_f32_e32 v98, v223, v98
	v_add_f32_e32 v98, v172, v98
	v_add_f32_e32 v98, v173, v98
	v_mfma_f32_32x32x16_bf16 v[114:129], v[242:245], v[130:133], v[114:129]
	v_exp_f32_e32 v204, v104
	v_add_f32_e32 v98, v174, v98
	v_exp_f32_e32 v205, v105
	v_add_f32_e32 v98, v175, v98
	v_exp_f32_e32 v206, v106
	v_add_f32_e32 v98, v176, v98
	v_exp_f32_e32 v207, v107
	v_add_f32_e32 v98, v177, v98
	v_add_f32_e32 v98, v204, v98
	v_add_f32_e32 v98, v205, v98
	v_add_f32_e32 v98, v206, v98
	v_add_f32_e32 v98, v207, v98
	v_add_f32_e32 v98, v224, v98
	v_add_f32_e32 v98, v225, v98
	v_add_f32_e32 v98, v226, v98
	v_add_f32_e32 v98, v227, v98
	v_add_f32_e32 v98, v112, v98
	v_cvt_pk_bf16_f32 v100, v208, v209
	v_cvt_pk_bf16_f32 v101, v210, v211
	v_cvt_pk_bf16_f32 v102, v212, v213
	v_cvt_pk_bf16_f32 v103, v214, v215
	v_cvt_pk_bf16_f32 v104, v216, v217
	v_cvt_pk_bf16_f32 v105, v218, v219
	v_cvt_pk_bf16_f32 v106, v220, v221
	v_cvt_pk_bf16_f32 v107, v222, v223
	v_cvt_pk_bf16_f32 v108, v172, v173
	v_cvt_pk_bf16_f32 v109, v174, v175
	v_cvt_pk_bf16_f32 v110, v176, v177
	v_cvt_pk_bf16_f32 v111, v204, v205
	v_cvt_pk_bf16_f32 v172, v206, v207
	v_cvt_pk_bf16_f32 v173, v224, v225
	v_cvt_pk_bf16_f32 v174, v226, v227
	v_cvt_pk_bf16_f32 v175, v112, v113
	v_add_u32_e32 v112, s19, v182
	ds_read_b64_tr_b16 v[204:205], v112 offset:0
	ds_read_b64_tr_b16 v[206:207], v112 offset:0x800
	ds_read_b64_tr_b16 v[208:209], v112 offset:0x1000
	ds_read_b64_tr_b16 v[210:211], v112 offset:0x1800
	ds_read_b64_tr_b16 v[212:213], v112 offset:0x2000
	ds_read_b64_tr_b16 v[214:215], v112 offset:0x2800
	ds_read_b64_tr_b16 v[216:217], v112 offset:0x3000
	ds_read_b64_tr_b16 v[218:219], v112 offset:0x3800
	v_add_f32_e32 v98, v113, v98
	s_waitcnt lgkmcnt(0)
; #define SBAR() __builtin_amdgcn_sched_barrier(0)
; __device__ __forceinline__ float max3f(float a, float b, float c) { return __builtin_fmaxf(__builtin_fmaxf(a, b), c); }
; template <bool FIRST, bool MLA>
; __device__ __forceinline__ void partialSM(f32x16& p0, f32x16& p1, f32x16& negm, float& m_reg, float& alpha) {
;   float a = max3f(p0[0], p0[1], p1[0]), b = max3f(p0[2], p0[3], p1[1]); a = max3f(a, p1[2], p1[3]);
; #pragma unroll
;   for (int r = 4; r < 16; r += 4) { a = max3f(a, p0[r], p0[r + 1]); b = max3f(b, p0[r + 2], p0[r + 3]); a = max3f(a, p1[r], p1[r + 1]); b = max3f(b, p1[r + 2], p1[r + 3]); }
;   float pmax = fmaxf(a, b);
;   { auto rr = __builtin_amdgcn_permlane32_swap(__float_as_uint(pmax), __float_as_uint(pmax), false, false);
;     pmax = fmaxf(__uint_as_float(rr[0]), __uint_as_float(rr[1])); }
;   alpha = 1.f;
;   if constexpr (MLA) {
;     if (FIRST) m_reg = pmax;
;     else if (!__builtin_expect(__all(pmax - m_reg <= THR2), 1)) { const float mn = fmaxf(m_reg, pmax); alpha = __builtin_amdgcn_exp2f(m_reg - mn); m_reg = mn; }
; #pragma unroll
;     for (int r = 0; r < 16; ++r) { p0[r] -= m_reg; p1[r] -= m_reg; }
;   } else
;   if (FIRST || __builtin_expect(__any(pmax > THR2), 0)) {
; template <int D0> __device__ __forceinline__ void pv_one(f32x16& od, int vb, bf16x8 pa0, bf16x8 pa1, bf16x8 pa2, bf16x8 pa3) {
;   const s16x4 l0 = tr_read<v_rd_off(D0, 0, 0)>(vb), h0 = tr_read<v_rd_off(D0, 0, 1)>(vb), l1 = tr_read<v_rd_off(D0, 1, 0)>(vb), h1 = tr_read<v_rd_off(D0, 1, 1)>(vb);
;   const s16x4 l2 = tr_read<v_rd_off(D0, 2, 0)>(vb), h2 = tr_read<v_rd_off(D0, 2, 1)>(vb), l3 = tr_read<v_rd_off(D0, 3, 0)>(vb), h3 = tr_read<v_rd_off(D0, 3, 1)>(vb);
;   asm volatile("s_waitcnt lgkmcnt(0)" ::: "memory"); SBAR();
;     ...
;   od = __builtin_amdgcn_mfma_f32_32x32x16_bf16(pa0, PK(l0, h0), od, 0, 0, 0);
;   od = __builtin_amdgcn_mfma_f32_32x32x16_bf16(pa1, PK(l1, h1), od, 0, 0, 0);
;   od = __builtin_amdgcn_mfma_f32_32x32x16_bf16(pa2, PK(l2, h2), od, 0, 0, 0);
;   od = __builtin_amdgcn_mfma_f32_32x32x16_bf16(pa3, PK(l3, h3), od, 0, 0, 0);
;     ...
; }
; __device__ __forceinline__ void pv_d0(f32x16* o, int vb, bf16x8 pa0, bf16x8 pa1, bf16x8 pa2, bf16x8 pa3) {
;   pv_one<0>(o[0], vb, pa0, pa1, pa2, pa3); pv_one<1>(o[1], vb, pa0, pa1, pa2, pa3); pv_one<2>(o[2], vb, pa0, pa1, pa2, pa3); pv_one<3>(o[3], vb, pa0, pa1, pa2, pa3);
	v_mov_b32_e32 v99, v98
	s_nop 1
	v_permlane32_swap_b32_e32 v98, v99
	v_permlane32_swap_b32_e32 v100, v102
	v_permlane32_swap_b32_e32 v172, v174
	v_permlane32_swap_b32_e32 v101, v103
	v_permlane32_swap_b32_e32 v104, v106
	v_permlane32_swap_b32_e32 v105, v107
	v_permlane32_swap_b32_e32 v108, v110
	v_permlane32_swap_b32_e32 v109, v111
	v_permlane32_swap_b32_e32 v173, v175
	v_mfma_f32_32x32x16_bf16 v[2:17], v[100:103], v[204:207], v[2:17]
	ds_read_b64_tr_b16 v[204:205], v112 offset:0x200
	ds_read_b64_tr_b16 v[206:207], v112 offset:0xa00
	v_mfma_f32_32x32x16_bf16 v[2:17], v[104:107], v[208:211], v[2:17]
	ds_read_b64_tr_b16 v[208:209], v112 offset:0x1200
	ds_read_b64_tr_b16 v[210:211], v112 offset:0x1a00
	v_mfma_f32_32x32x16_bf16 v[2:17], v[108:111], v[212:215], v[2:17]
	ds_read_b64_tr_b16 v[212:213], v112 offset:0x2200
	ds_read_b64_tr_b16 v[214:215], v112 offset:0x2a00
	v_mfma_f32_32x32x16_bf16 v[2:17], v[172:175], v[216:219], v[2:17]
	ds_read_b64_tr_b16 v[216:217], v112 offset:0x3200
	ds_read_b64_tr_b16 v[218:219], v112 offset:0x3a00
	s_waitcnt lgkmcnt(6)
	v_mfma_f32_32x32x16_bf16 v[50:65], v[100:103], v[204:207], v[50:65]
	ds_read_b64_tr_b16 v[204:205], v112 offset:0x400
	ds_read_b64_tr_b16 v[206:207], v112 offset:0xc00
	s_waitcnt lgkmcnt(6)
	v_mfma_f32_32x32x16_bf16 v[50:65], v[104:107], v[208:211], v[50:65]
	ds_read_b64_tr_b16 v[208:209], v112 offset:0x1400
	ds_read_b64_tr_b16 v[210:211], v112 offset:0x1c00
	s_waitcnt lgkmcnt(6)
	v_mfma_f32_32x32x16_bf16 v[50:65], v[108:111], v[212:215], v[50:65]
	ds_read_b64_tr_b16 v[212:213], v112 offset:0x2400
	ds_read_b64_tr_b16 v[214:215], v112 offset:0x2c00
	s_waitcnt lgkmcnt(6)
	v_mfma_f32_32x32x16_bf16 v[50:65], v[172:175], v[216:219], v[50:65]
	ds_read_b64_tr_b16 v[216:217], v112 offset:0x3400
	ds_read_b64_tr_b16 v[218:219], v112 offset:0x3c00
	s_waitcnt lgkmcnt(6)
	v_mfma_f32_32x32x16_bf16 v[34:49], v[100:103], v[204:207], v[34:49]
	ds_read_b64_tr_b16 v[204:205], v112 offset:0x600
	ds_read_b64_tr_b16 v[206:207], v112 offset:0xe00
	s_waitcnt lgkmcnt(6)
	v_mfma_f32_32x32x16_bf16 v[34:49], v[104:107], v[208:211], v[34:49]
	ds_read_b64_tr_b16 v[208:209], v112 offset:0x1600
	ds_read_b64_tr_b16 v[210:211], v112 offset:0x1e00
	s_waitcnt lgkmcnt(6)
	v_mfma_f32_32x32x16_bf16 v[34:49], v[108:111], v[212:215], v[34:49]
	ds_read_b64_tr_b16 v[212:213], v112 offset:0x2600
	ds_read_b64_tr_b16 v[214:215], v112 offset:0x2e00
	s_waitcnt lgkmcnt(6)
	v_mfma_f32_32x32x16_bf16 v[34:49], v[172:175], v[216:219], v[34:49]
	ds_read_b64_tr_b16 v[216:217], v112 offset:0x3600
	ds_read_b64_tr_b16 v[218:219], v112 offset:0x3e00
	s_waitcnt lgkmcnt(6)
	v_mfma_f32_32x32x16_bf16 v[18:33], v[100:103], v[204:207], v[18:33]
	v_max_f32_e32 v100, v115, v115
	v_max_f32_e32 v101, v114, v114
	v_max_f32_e32 v100, v101, v100
	v_max3_f32 v101, v116, v117, v83
	v_max3_f32 v100, v100, v82, v84
	v_max3_f32 v100, v100, v85, v118
	v_max3_f32 v101, v101, v120, v121
	s_waitcnt lgkmcnt(4)
	v_mfma_f32_32x32x16_bf16 v[18:33], v[104:107], v[208:211], v[18:33]
	v_max3_f32 v100, v100, v119, v86
	v_max3_f32 v101, v101, v88, v89
	v_max3_f32 v100, v100, v87, v122
	v_max3_f32 v101, v101, v124, v125
	v_max3_f32 v100, v100, v123, v90
	v_max3_f32 v101, v101, v92, v93
	v_max3_f32 v100, v100, v91, v126
	s_waitcnt lgkmcnt(2)
	v_mfma_f32_32x32x16_bf16 v[18:33], v[108:111], v[212:215], v[18:33]
	v_max3_f32 v101, v101, v128, v129
	v_max3_f32 v100, v100, v127, v94
	v_max3_f32 v101, v101, v96, v97
	v_max3_f32 v100, v100, v95, v101
	v_mov_b32_e32 v101, v100
	s_nop 1
	v_permlane32_swap_b32_e32 v100, v101
	s_waitcnt lgkmcnt(0)
	v_mfma_f32_32x32x16_bf16 v[18:33], v[172:175], v[216:219], v[18:33]
	v_max_f32_e32 v101, v101, v101
	v_max_f32_e32 v100, v100, v100
	v_max_f32_e32 v100, v100, v101
	v_cmp_lt_f32_e32 vcc, s40, v100
	v_mov_b32_e32 v172, 1.0
	s_cbranch_vccnz .LBB0_138
	v_cmp_gt_f32_e32 vcc, 1.0, v172
	s_cbranch_vccz .LBB0_135
